# v5 plus: drop redundant vmcnt(0) before accumulator zeroing in GEMM tile prologues so the first-stage DMA overlaps the zeroing
# speedup vs baseline: 1.0009x; 1.0009x over previous
; DI void vm_wait0() { asm volatile("s_waitcnt vmcnt(0)" ::: "memory"); }
;   DI unsigned rowoff(int m) const { int combo = m >> 9, n = m & 511, b = combo >> 1, g = combo & 1; return (unsigned)((b * SEQ + 16 * n) * EIN + col0 + g * 64); }
;   DI unsigned koff(int k) const { return (unsigned)((k >> 6) * EIN + (k & 63)); }
; DI void dma16(const void* g, unsigned char* l) { __builtin_amdgcn_global_load_lds((const unsigned*)g, (lds_u32_t*)(unsigned)(size_t)l, 16, 0, 0); }
; template <class AF, class EF>
; DI void gemm_run(unsigned char* lds, int wv, const AF& af, const bf16_t* __restrict__ Bt, int ldb, int M, int N, int K, const EF& ef, int blk_off) {
;     ...
;   for (int tile_ = first; tile_ < ntl_eff; tile_ += tstep) {
;     int nt, mt;
;     if (xmap) { nt = tile_ % ntiles; mt = (tile_ / ntiles) * 8 + ((int)blockIdx.x & 7); }
;     else { nt = tile_ % ntiles; mt = tile_ / ntiles; }
;     const int m0 = mt << 8, n0 = nt << 8;
;     f32x4 acc[4][8];
; #pragma unroll
;     for (int i = 0; i < 4; ++i)
; #pragma unroll
;       for (int j = 0; j < 8; ++j) acc[i][j] = (f32x4){0.f, 0.f, 0.f, 0.f};
;     unsigned aoff[4], boff[4];
;     const bf16_t* Ab = af.base();
; #pragma unroll
;     for (int i = 0; i < 4; ++i) {
;       int row = crow + 64 * i;
;       aoff[i] = af.rowoff(m0 + row);
;       int n = n0 + row; n = n < N ? n : N - 1;
;       boff[i] = (unsigned)(n * ldb + cch);
;     }
;     __syncthreads();
; #pragma unroll
;     for (int i = 0; i < 4; ++i) {
;       dma16(Ab + aoff[i] + af.koff(cch), sBase + 32768 + (i * 512 + tid) * 16);
;       dma16(Bt + boff[i], sBase + (i * 512 + tid) * 16);
;     }
;     vm_wait0();
;     __syncthreads();
.LBB0_119:
	s_mul_hi_i32 s4, s2, 0x2aaaaaab
	s_lshr_b32 s5, s4, 31
	s_ashr_i32 s4, s4, 1
	s_add_i32 s7, s4, s5
	s_lshl_b32 s4, s7, 3
	s_or_b32 s6, s4, s78
	v_readlane_b32 s4, v254, 34
	v_readlane_b32 s5, v254, 35
	s_and_b64 s[4:5], s[4:5], exec
	s_cselect_b32 s4, s6, s7
	s_mul_i32 s7, s7, 12
	s_lshl_b32 s6, s4, 8
	s_sub_i32 s4, s2, s7
	s_lshl_b32 s7, s4, 8
	v_add_u32_e32 v3, s7, v164
	v_min_i32_e32 v3, 0xbff, v3
	v_lshl_or_b32 v6, v3, 10, v141
	v_add_u32_e32 v3, s7, v165
	v_min_i32_e32 v3, 0xbff, v3
	v_add_u32_e32 v2, s7, v139
	v_lshl_or_b32 v10, v3, 10, v141
	v_add_u32_e32 v3, s7, v166
	v_add_lshl_u32 v0, s6, v139, 10
	v_min_i32_e32 v2, 0xbff, v2
	v_min_i32_e32 v3, 0xbff, v3
	v_lshl_or_b32 v2, v2, 10, v141
	v_lshl_or_b32 v14, v3, 10, v141
	v_lshlrev_b64 v[16:17], 1, v[0:1]
	v_readfirstlane_b32 s4, v167
	v_mov_b32_e32 v3, v1
	v_add_lshl_u32 v4, s6, v164, 10
	v_lshl_add_u64 v[18:19], v[134:135], 0, v[16:17]
	s_mov_b32 m0, s4
	v_lshlrev_b64 v[2:3], 1, v[2:3]
	v_readfirstlane_b32 s4, v168
	v_mov_b32_e32 v5, v1
	s_waitcnt lgkmcnt(0)
	s_barrier
	global_load_lds_dwordx4 v[18:19], off
	v_lshl_add_u64 v[18:19], s[8:9], 0, v[2:3]
	s_mov_b32 m0, s4
	v_lshlrev_b64 v[4:5], 1, v[4:5]
	v_readfirstlane_b32 s4, v169
	v_mov_b32_e32 v7, v1
	v_add_lshl_u32 v8, s6, v165, 10
	global_load_lds_dwordx4 v[18:19], off
	v_lshl_add_u64 v[18:19], v[134:135], 0, v[4:5]
	s_mov_b32 m0, s4
	v_lshlrev_b64 v[6:7], 1, v[6:7]
	v_readfirstlane_b32 s4, v170
	v_mov_b32_e32 v9, v1
	global_load_lds_dwordx4 v[18:19], off
	v_lshl_add_u64 v[18:19], s[8:9], 0, v[6:7]
	s_mov_b32 m0, s4
	v_lshlrev_b64 v[8:9], 1, v[8:9]
	v_readfirstlane_b32 s4, v171
	v_mov_b32_e32 v11, v1
	v_add_lshl_u32 v12, s6, v166, 10
	global_load_lds_dwordx4 v[18:19], off
	v_lshl_add_u64 v[18:19], v[134:135], 0, v[8:9]
	s_mov_b32 m0, s4
	v_lshlrev_b64 v[10:11], 1, v[10:11]
	v_readfirstlane_b32 s4, v172
	v_mov_b32_e32 v13, v1
	global_load_lds_dwordx4 v[18:19], off
	v_lshl_add_u64 v[18:19], s[8:9], 0, v[10:11]
	s_mov_b32 m0, s4
	v_lshlrev_b64 v[12:13], 1, v[12:13]
	v_readfirstlane_b32 s4, v173
	v_mov_b32_e32 v15, v1
	global_load_lds_dwordx4 v[18:19], off
	v_lshl_add_u64 v[18:19], v[134:135], 0, v[12:13]
	s_mov_b32 m0, s4
	v_lshlrev_b64 v[14:15], 1, v[14:15]
	v_readfirstlane_b32 s4, v174
	global_load_lds_dwordx4 v[18:19], off
	v_lshl_add_u64 v[18:19], s[8:9], 0, v[14:15]
	s_mov_b32 m0, s4
	v_lshl_add_u64 v[152:153], s[12:13], 0, v[2:3]
	global_load_lds_dwordx4 v[18:19], off
	v_mov_b32_e32 v2, 0
	v_lshl_add_u64 v[146:147], s[12:13], 0, v[14:15]
	v_lshl_add_u64 v[148:149], s[12:13], 0, v[10:11]
	v_lshl_add_u64 v[150:151], s[12:13], 0, v[6:7]
	v_lshl_add_u64 v[154:155], v[144:145], 0, v[12:13]
	v_lshl_add_u64 v[156:157], v[144:145], 0, v[8:9]
	v_lshl_add_u64 v[158:159], v[144:145], 0, v[4:5]
	v_lshl_add_u64 v[160:161], v[144:145], 0, v[16:17]
	s_mov_b64 s[4:5], 0
	s_mov_b32 s14, 0x10000
	v_mov_b32_e32 v3, v2
	v_mov_b32_e32 v4, v2
	v_mov_b32_e32 v5, v2
	v_mov_b32_e32 v6, v2
	v_mov_b32_e32 v7, v2
	v_mov_b32_e32 v8, v2
	v_mov_b32_e32 v9, v2
	v_mov_b32_e32 v18, v2
	v_mov_b32_e32 v19, v2
	v_mov_b32_e32 v20, v2
	v_mov_b32_e32 v21, v2
	v_mov_b32_e32 v26, v2
	v_mov_b32_e32 v27, v2
	v_mov_b32_e32 v28, v2
	v_mov_b32_e32 v29, v2
	v_mov_b32_e32 v34, v2
	v_mov_b32_e32 v35, v2
	v_mov_b32_e32 v36, v2
	v_mov_b32_e32 v37, v2
	v_mov_b32_e32 v42, v2
	v_mov_b32_e32 v43, v2
	v_mov_b32_e32 v44, v2
	v_mov_b32_e32 v45, v2
	v_mov_b32_e32 v50, v2
	v_mov_b32_e32 v51, v2
	v_mov_b32_e32 v52, v2
	v_mov_b32_e32 v53, v2
	v_mov_b32_e32 v58, v2
	v_mov_b32_e32 v59, v2
	v_mov_b32_e32 v60, v2
	v_mov_b32_e32 v61, v2
	v_mov_b32_e32 v66, v2
	v_mov_b32_e32 v67, v2
	v_mov_b32_e32 v68, v2
	v_mov_b32_e32 v69, v2
	v_mov_b32_e32 v74, v2
	v_mov_b32_e32 v75, v2
	v_mov_b32_e32 v76, v2
	v_mov_b32_e32 v77, v2
	v_mov_b32_e32 v82, v2
	v_mov_b32_e32 v83, v2
	v_mov_b32_e32 v84, v2
	v_mov_b32_e32 v85, v2
	v_mov_b32_e32 v90, v2
	v_mov_b32_e32 v91, v2
	v_mov_b32_e32 v92, v2
	v_mov_b32_e32 v93, v2
	v_mov_b32_e32 v98, v2
	v_mov_b32_e32 v99, v2
	v_mov_b32_e32 v100, v2
	v_mov_b32_e32 v101, v2
	v_mov_b32_e32 v106, v2
	v_mov_b32_e32 v107, v2
	v_mov_b32_e32 v108, v2
	v_mov_b32_e32 v109, v2
	v_mov_b32_e32 v114, v2
	v_mov_b32_e32 v115, v2
	v_mov_b32_e32 v116, v2
	v_mov_b32_e32 v117, v2
	v_mov_b32_e32 v122, v2
	v_mov_b32_e32 v123, v2
	v_mov_b32_e32 v124, v2
	v_mov_b32_e32 v125, v2
	v_mov_b32_e32 v70, v2
	v_mov_b32_e32 v71, v2
	v_mov_b32_e32 v72, v2
	v_mov_b32_e32 v73, v2
	v_mov_b32_e32 v78, v2
	v_mov_b32_e32 v79, v2
	v_mov_b32_e32 v80, v2
	v_mov_b32_e32 v81, v2
	v_mov_b32_e32 v86, v2
	v_mov_b32_e32 v87, v2
	v_mov_b32_e32 v88, v2
	v_mov_b32_e32 v89, v2
	v_mov_b32_e32 v94, v2
	v_mov_b32_e32 v95, v2
	v_mov_b32_e32 v96, v2
	v_mov_b32_e32 v97, v2
	v_mov_b32_e32 v102, v2
	v_mov_b32_e32 v103, v2
	v_mov_b32_e32 v104, v2
	v_mov_b32_e32 v105, v2
	v_mov_b32_e32 v110, v2
	v_mov_b32_e32 v111, v2
	v_mov_b32_e32 v112, v2
	v_mov_b32_e32 v113, v2
	v_mov_b32_e32 v118, v2
	v_mov_b32_e32 v119, v2
	v_mov_b32_e32 v120, v2
	v_mov_b32_e32 v121, v2
	v_mov_b32_e32 v126, v2
	v_mov_b32_e32 v127, v2
	v_mov_b32_e32 v128, v2
	v_mov_b32_e32 v129, v2
	v_mov_b32_e32 v62, v2
	v_mov_b32_e32 v63, v2
	v_mov_b32_e32 v64, v2
	v_mov_b32_e32 v65, v2
	v_mov_b32_e32 v54, v2
	v_mov_b32_e32 v55, v2
	v_mov_b32_e32 v56, v2
	v_mov_b32_e32 v57, v2
	v_mov_b32_e32 v46, v2
	v_mov_b32_e32 v47, v2
	v_mov_b32_e32 v48, v2
	v_mov_b32_e32 v49, v2
	v_mov_b32_e32 v38, v2
	v_mov_b32_e32 v39, v2
	v_mov_b32_e32 v40, v2
	v_mov_b32_e32 v41, v2
	v_mov_b32_e32 v30, v2
	v_mov_b32_e32 v31, v2
	v_mov_b32_e32 v32, v2
	v_mov_b32_e32 v33, v2
	v_mov_b32_e32 v22, v2
	v_mov_b32_e32 v23, v2
	v_mov_b32_e32 v24, v2
	v_mov_b32_e32 v25, v2
	v_mov_b32_e32 v14, v2
	v_mov_b32_e32 v15, v2
	v_mov_b32_e32 v16, v2
	v_mov_b32_e32 v17, v2
	v_mov_b32_e32 v10, v2
	v_mov_b32_e32 v11, v2
	v_mov_b32_e32 v12, v2
	v_mov_b32_e32 v13, v2
	s_waitcnt vmcnt(0) lgkmcnt(0)
	s_barrier
	s_branch .LBB0_121

; DI void vm_wait0() { asm volatile("s_waitcnt vmcnt(0)" ::: "memory"); }
;   DI unsigned rowoff(int m) const { int combo = m >> 9, n = m & 511, b = combo >> 1, g = combo & 1; return (unsigned)((b * SEQ + 16 * n) * EIN + col0 + g * 64); }
;   DI unsigned koff(int k) const { return (unsigned)((k >> 6) * EIN + (k & 63)); }
; DI void dma16(const void* g, unsigned char* l) { __builtin_amdgcn_global_load_lds((const unsigned*)g, (lds_u32_t*)(unsigned)(size_t)l, 16, 0, 0); }
; template <class AF, class EF>
; DI void gemm_run(unsigned char* lds, int wv, const AF& af, const bf16_t* __restrict__ Bt, int ldb, int M, int N, int K, const EF& ef, int blk_off) {
;     ...
;   for (int tile_ = first; tile_ < ntl_eff; tile_ += tstep) {
;     int nt, mt;
;     if (xmap) { nt = tile_ % ntiles; mt = (tile_ / ntiles) * 8 + ((int)blockIdx.x & 7); }
;     else { nt = tile_ % ntiles; mt = tile_ / ntiles; }
;     const int m0 = mt << 8, n0 = nt << 8;
;     f32x4 acc[4][8];
; #pragma unroll
;     for (int i = 0; i < 4; ++i)
; #pragma unroll
;       for (int j = 0; j < 8; ++j) acc[i][j] = (f32x4){0.f, 0.f, 0.f, 0.f};
;     unsigned aoff[4], boff[4];
;     const bf16_t* Ab = af.base();
; #pragma unroll
;     for (int i = 0; i < 4; ++i) {
;       int row = crow + 64 * i;
;       aoff[i] = af.rowoff(m0 + row);
;       int n = n0 + row; n = n < N ? n : N - 1;
;       boff[i] = (unsigned)(n * ldb + cch);
;     }
;     __syncthreads();
; #pragma unroll
;     for (int i = 0; i < 4; ++i) {
;       dma16(Ab + aoff[i] + af.koff(cch), sBase + 32768 + (i * 512 + tid) * 16);
;       dma16(Bt + boff[i], sBase + (i * 512 + tid) * 16);
;     }
;     vm_wait0();
;     __syncthreads();
.LBB0_260:
	s_mul_hi_i32 s4, s2, 0x66666667
	s_lshr_b32 s5, s4, 31
	s_ashr_i32 s4, s4, 2
	s_add_i32 s6, s4, s5
	s_lshl_b32 s4, s6, 3
	s_or_b32 s7, s4, s78
	v_readlane_b32 s4, v254, 34
	v_readlane_b32 s5, v254, 35
	s_and_b64 s[4:5], s[4:5], exec
	s_cselect_b32 s4, s7, s6
	s_mul_i32 s6, s6, 10
	s_lshl_b32 s7, s4, 8
	s_sub_i32 s4, s2, s6
	s_lshl_b32 s6, s4, 8
	v_add_u32_e32 v3, s6, v164
	v_min_i32_e32 v3, 0x9df, v3
	v_lshl_or_b32 v6, v3, 10, v141
	v_add_u32_e32 v3, s6, v165
	v_min_i32_e32 v3, 0x9df, v3
	v_add_u32_e32 v2, s6, v139
	v_lshl_or_b32 v10, v3, 10, v141
	v_add_u32_e32 v3, s6, v166
	v_add_lshl_u32 v0, s7, v139, 10
	v_min_i32_e32 v2, 0x9df, v2
	v_min_i32_e32 v3, 0x9df, v3
	v_lshl_or_b32 v2, v2, 10, v141
	v_lshl_or_b32 v14, v3, 10, v141
	v_lshlrev_b64 v[16:17], 1, v[0:1]
	v_readfirstlane_b32 s4, v167
	v_mov_b32_e32 v3, v1
	v_add_lshl_u32 v4, s7, v164, 10
	v_lshl_add_u64 v[18:19], v[134:135], 0, v[16:17]
	s_mov_b32 m0, s4
	v_lshlrev_b64 v[2:3], 1, v[2:3]
	v_readfirstlane_b32 s4, v168
	v_mov_b32_e32 v5, v1
	s_waitcnt lgkmcnt(0)
	s_barrier
	global_load_lds_dwordx4 v[18:19], off
	v_lshl_add_u64 v[18:19], s[8:9], 0, v[2:3]
	s_mov_b32 m0, s4
	v_lshlrev_b64 v[4:5], 1, v[4:5]
	v_readfirstlane_b32 s4, v169
	v_mov_b32_e32 v7, v1
	v_add_lshl_u32 v8, s7, v165, 10
	global_load_lds_dwordx4 v[18:19], off
	v_lshl_add_u64 v[18:19], v[134:135], 0, v[4:5]
	s_mov_b32 m0, s4
	v_lshlrev_b64 v[6:7], 1, v[6:7]
	v_readfirstlane_b32 s4, v170
	v_mov_b32_e32 v9, v1
	global_load_lds_dwordx4 v[18:19], off
	v_lshl_add_u64 v[18:19], s[8:9], 0, v[6:7]
	s_mov_b32 m0, s4
	v_lshlrev_b64 v[8:9], 1, v[8:9]
	v_readfirstlane_b32 s4, v171
	v_mov_b32_e32 v11, v1
	v_add_lshl_u32 v12, s7, v166, 10
	global_load_lds_dwordx4 v[18:19], off
	v_lshl_add_u64 v[18:19], v[134:135], 0, v[8:9]
	s_mov_b32 m0, s4
	v_lshlrev_b64 v[10:11], 1, v[10:11]
	v_readfirstlane_b32 s4, v172
	v_mov_b32_e32 v13, v1
	global_load_lds_dwordx4 v[18:19], off
	v_lshl_add_u64 v[18:19], s[8:9], 0, v[10:11]
	s_mov_b32 m0, s4
	v_lshlrev_b64 v[12:13], 1, v[12:13]
	v_readfirstlane_b32 s4, v173
	v_mov_b32_e32 v15, v1
	global_load_lds_dwordx4 v[18:19], off
	v_lshl_add_u64 v[18:19], v[134:135], 0, v[12:13]
	s_mov_b32 m0, s4
	v_lshlrev_b64 v[14:15], 1, v[14:15]
	v_readfirstlane_b32 s4, v174
	global_load_lds_dwordx4 v[18:19], off
	v_lshl_add_u64 v[18:19], s[8:9], 0, v[14:15]
	s_mov_b32 m0, s4
	v_lshl_add_u64 v[152:153], s[14:15], 0, v[2:3]
	global_load_lds_dwordx4 v[18:19], off
	v_mov_b32_e32 v2, 0
	v_lshl_add_u64 v[146:147], s[14:15], 0, v[14:15]
	v_lshl_add_u64 v[148:149], s[14:15], 0, v[10:11]
	v_lshl_add_u64 v[150:151], s[14:15], 0, v[6:7]
	v_lshl_add_u64 v[154:155], v[144:145], 0, v[12:13]
	v_lshl_add_u64 v[156:157], v[144:145], 0, v[8:9]
	v_lshl_add_u64 v[158:159], v[144:145], 0, v[4:5]
	v_lshl_add_u64 v[160:161], v[144:145], 0, v[16:17]
	s_mov_b64 s[4:5], 0
	s_mov_b32 s16, 0x10000
	v_mov_b32_e32 v3, v2
	v_mov_b32_e32 v4, v2
	v_mov_b32_e32 v5, v2
	v_mov_b32_e32 v14, v2
	v_mov_b32_e32 v15, v2
	v_mov_b32_e32 v16, v2
	v_mov_b32_e32 v17, v2
	v_mov_b32_e32 v22, v2
	v_mov_b32_e32 v23, v2
	v_mov_b32_e32 v24, v2
	v_mov_b32_e32 v25, v2
	v_mov_b32_e32 v30, v2
	v_mov_b32_e32 v31, v2
	v_mov_b32_e32 v32, v2
	v_mov_b32_e32 v33, v2
	v_mov_b32_e32 v38, v2
	v_mov_b32_e32 v39, v2
	v_mov_b32_e32 v40, v2
	v_mov_b32_e32 v41, v2
	v_mov_b32_e32 v46, v2
	v_mov_b32_e32 v47, v2
	v_mov_b32_e32 v48, v2
	v_mov_b32_e32 v49, v2
	v_mov_b32_e32 v54, v2
	v_mov_b32_e32 v55, v2
	v_mov_b32_e32 v56, v2
	v_mov_b32_e32 v57, v2
	v_mov_b32_e32 v62, v2
	v_mov_b32_e32 v63, v2
	v_mov_b32_e32 v64, v2
	v_mov_b32_e32 v65, v2
	v_mov_b32_e32 v66, v2
	v_mov_b32_e32 v67, v2
	v_mov_b32_e32 v68, v2
	v_mov_b32_e32 v69, v2
	v_mov_b32_e32 v74, v2
	v_mov_b32_e32 v75, v2
	v_mov_b32_e32 v76, v2
	v_mov_b32_e32 v77, v2
	v_mov_b32_e32 v82, v2
	v_mov_b32_e32 v83, v2
	v_mov_b32_e32 v84, v2
	v_mov_b32_e32 v85, v2
	v_mov_b32_e32 v90, v2
	v_mov_b32_e32 v91, v2
	v_mov_b32_e32 v92, v2
	v_mov_b32_e32 v93, v2
	v_mov_b32_e32 v98, v2
	v_mov_b32_e32 v99, v2
	v_mov_b32_e32 v100, v2
	v_mov_b32_e32 v101, v2
	v_mov_b32_e32 v106, v2
	v_mov_b32_e32 v107, v2
	v_mov_b32_e32 v108, v2
	v_mov_b32_e32 v109, v2
	v_mov_b32_e32 v114, v2
	v_mov_b32_e32 v115, v2
	v_mov_b32_e32 v116, v2
	v_mov_b32_e32 v117, v2
	v_mov_b32_e32 v122, v2
	v_mov_b32_e32 v123, v2
	v_mov_b32_e32 v124, v2
	v_mov_b32_e32 v125, v2
	v_mov_b32_e32 v70, v2
	v_mov_b32_e32 v71, v2
	v_mov_b32_e32 v72, v2
	v_mov_b32_e32 v73, v2
	v_mov_b32_e32 v78, v2
	v_mov_b32_e32 v79, v2
	v_mov_b32_e32 v80, v2
	v_mov_b32_e32 v81, v2
	v_mov_b32_e32 v86, v2
	v_mov_b32_e32 v87, v2
	v_mov_b32_e32 v88, v2
	v_mov_b32_e32 v89, v2
	v_mov_b32_e32 v94, v2
	v_mov_b32_e32 v95, v2
	v_mov_b32_e32 v96, v2
	v_mov_b32_e32 v97, v2
	v_mov_b32_e32 v102, v2
	v_mov_b32_e32 v103, v2
	v_mov_b32_e32 v104, v2
	v_mov_b32_e32 v105, v2
	v_mov_b32_e32 v110, v2
	v_mov_b32_e32 v111, v2
	v_mov_b32_e32 v112, v2
	v_mov_b32_e32 v113, v2
	v_mov_b32_e32 v118, v2
	v_mov_b32_e32 v119, v2
	v_mov_b32_e32 v120, v2
	v_mov_b32_e32 v121, v2
	v_mov_b32_e32 v126, v2
	v_mov_b32_e32 v127, v2
	v_mov_b32_e32 v128, v2
	v_mov_b32_e32 v129, v2
	v_mov_b32_e32 v58, v2
	v_mov_b32_e32 v59, v2
	v_mov_b32_e32 v60, v2
	v_mov_b32_e32 v61, v2
	v_mov_b32_e32 v50, v2
	v_mov_b32_e32 v51, v2
	v_mov_b32_e32 v52, v2
	v_mov_b32_e32 v53, v2
	v_mov_b32_e32 v42, v2
	v_mov_b32_e32 v43, v2
	v_mov_b32_e32 v44, v2
	v_mov_b32_e32 v45, v2
	v_mov_b32_e32 v34, v2
	v_mov_b32_e32 v35, v2
	v_mov_b32_e32 v36, v2
	v_mov_b32_e32 v37, v2
	v_mov_b32_e32 v26, v2
	v_mov_b32_e32 v27, v2
	v_mov_b32_e32 v28, v2
	v_mov_b32_e32 v29, v2
	v_mov_b32_e32 v18, v2
	v_mov_b32_e32 v19, v2
	v_mov_b32_e32 v20, v2
	v_mov_b32_e32 v21, v2
	v_mov_b32_e32 v10, v2
	v_mov_b32_e32 v11, v2
	v_mov_b32_e32 v12, v2
	v_mov_b32_e32 v13, v2
	v_mov_b32_e32 v6, v2
	v_mov_b32_e32 v7, v2
	v_mov_b32_e32 v8, v2
	v_mov_b32_e32 v9, v2
	s_waitcnt vmcnt(0) lgkmcnt(0)
	s_barrier
	s_branch .LBB0_262

; DI void vm_wait0() { asm volatile("s_waitcnt vmcnt(0)" ::: "memory"); }
;   DI unsigned rowoff(int m) const { int combo = m >> 9, n = m & 511, b = combo >> 1, g = combo & 1; return (unsigned)((b * SEQ + 16 * n) * EIN + col0 + g * 64); }
;   DI unsigned koff(int k) const { return (unsigned)((k >> 6) * EIN + (k & 63)); }
; DI void dma16(const void* g, unsigned char* l) { __builtin_amdgcn_global_load_lds((const unsigned*)g, (lds_u32_t*)(unsigned)(size_t)l, 16, 0, 0); }
; template <class AF, class EF>
; DI void gemm_run(unsigned char* lds, int wv, const AF& af, const bf16_t* __restrict__ Bt, int ldb, int M, int N, int K, const EF& ef, int blk_off) {
;     ...
;   for (int tile_ = first; tile_ < ntl_eff; tile_ += tstep) {
;     int nt, mt;
;     if (xmap) { nt = tile_ % ntiles; mt = (tile_ / ntiles) * 8 + ((int)blockIdx.x & 7); }
;     else { nt = tile_ % ntiles; mt = tile_ / ntiles; }
;     const int m0 = mt << 8, n0 = nt << 8;
;     f32x4 acc[4][8];
; #pragma unroll
;     for (int i = 0; i < 4; ++i)
; #pragma unroll
;       for (int j = 0; j < 8; ++j) acc[i][j] = (f32x4){0.f, 0.f, 0.f, 0.f};
;     unsigned aoff[4], boff[4];
;     const bf16_t* Ab = af.base();
; #pragma unroll
;     for (int i = 0; i < 4; ++i) {
;       int row = crow + 64 * i;
;       aoff[i] = af.rowoff(m0 + row);
;       int n = n0 + row; n = n < N ? n : N - 1;
;       boff[i] = (unsigned)(n * ldb + cch);
;     }
;     __syncthreads();
; #pragma unroll
;     for (int i = 0; i < 4; ++i) {
;       dma16(Ab + aoff[i] + af.koff(cch), sBase + 32768 + (i * 512 + tid) * 16);
;       dma16(Bt + boff[i], sBase + (i * 512 + tid) * 16);
;     }
;     vm_wait0();
;     __syncthreads();
.LBB0_699:
	s_lshl_b32 s2, s31, 3
	s_or_b32 s2, s2, s78
	s_and_b64 s[6:7], s[16:17], exec
	s_cselect_b32 s2, s2, s31
	s_lshl_b32 s8, s2, 8
	v_add_lshl_u32 v0, s8, v141, 8
	v_lshlrev_b64 v[8:9], 1, v[0:1]
	v_readfirstlane_b32 s2, v182
	v_add_lshl_u32 v2, s8, v163, 8
	v_lshl_add_u64 v[10:11], v[134:135], 0, v[8:9]
	s_mov_b32 m0, s2
	v_readfirstlane_b32 s2, v183
	v_mov_b32_e32 v3, v1
	s_barrier
	global_load_lds_dwordx4 v[10:11], off
	s_mov_b32 m0, s2
	v_lshlrev_b64 v[2:3], 1, v[2:3]
	v_readfirstlane_b32 s2, v184
	v_add_lshl_u32 v4, s8, v180, 8
	global_load_lds_dwordx4 v[138:139], off
	v_lshl_add_u64 v[10:11], v[134:135], 0, v[2:3]
	s_mov_b32 m0, s2
	v_readfirstlane_b32 s2, v185
	v_mov_b32_e32 v5, v1
	global_load_lds_dwordx4 v[10:11], off
	s_mov_b32 m0, s2
	v_lshlrev_b64 v[4:5], 1, v[4:5]
	v_readfirstlane_b32 s2, v186
	v_add_lshl_u32 v6, s8, v181, 8
	global_load_lds_dwordx4 v[142:143], off
	v_lshl_add_u64 v[10:11], v[134:135], 0, v[4:5]
	s_mov_b32 m0, s2
	v_readfirstlane_b32 s2, v187
	v_mov_b32_e32 v7, v1
	global_load_lds_dwordx4 v[10:11], off
	s_mov_b32 m0, s2
	v_lshlrev_b64 v[6:7], 1, v[6:7]
	v_readfirstlane_b32 s2, v188
	global_load_lds_dwordx4 v[146:147], off
	v_lshl_add_u64 v[10:11], v[134:135], 0, v[6:7]
	s_mov_b32 m0, s2
	v_readfirstlane_b32 s2, v189
	global_load_lds_dwordx4 v[10:11], off
	s_mov_b32 m0, s2
	v_lshl_add_u64 v[176:177], v[170:171], 0, v[2:3]
	global_load_lds_dwordx4 v[150:151], off
	v_mov_b32_e32 v2, 0
	v_lshl_add_u64 v[172:173], v[170:171], 0, v[6:7]
	v_lshl_add_u64 v[174:175], v[170:171], 0, v[4:5]
	v_lshl_add_u64 v[178:179], v[170:171], 0, v[8:9]
	s_mov_b64 s[6:7], 0
	s_mov_b32 s9, 0x10000
	v_mov_b32_e32 v3, v2
	v_mov_b32_e32 v4, v2
	v_mov_b32_e32 v5, v2
	v_mov_b32_e32 v6, v2
	v_mov_b32_e32 v7, v2
	v_mov_b32_e32 v8, v2
	v_mov_b32_e32 v9, v2
	v_mov_b32_e32 v14, v2
	v_mov_b32_e32 v15, v2
	v_mov_b32_e32 v16, v2
	v_mov_b32_e32 v17, v2
	v_mov_b32_e32 v26, v2
	v_mov_b32_e32 v27, v2
	v_mov_b32_e32 v28, v2
	v_mov_b32_e32 v29, v2
	v_mov_b32_e32 v34, v2
	v_mov_b32_e32 v35, v2
	v_mov_b32_e32 v36, v2
	v_mov_b32_e32 v37, v2
	v_mov_b32_e32 v42, v2
	v_mov_b32_e32 v43, v2
	v_mov_b32_e32 v44, v2
	v_mov_b32_e32 v45, v2
	v_mov_b32_e32 v50, v2
	v_mov_b32_e32 v51, v2
	v_mov_b32_e32 v52, v2
	v_mov_b32_e32 v53, v2
	v_mov_b32_e32 v58, v2
	v_mov_b32_e32 v59, v2
	v_mov_b32_e32 v60, v2
	v_mov_b32_e32 v61, v2
	v_mov_b32_e32 v66, v2
	v_mov_b32_e32 v67, v2
	v_mov_b32_e32 v68, v2
	v_mov_b32_e32 v69, v2
	v_mov_b32_e32 v74, v2
	v_mov_b32_e32 v75, v2
	v_mov_b32_e32 v76, v2
	v_mov_b32_e32 v77, v2
	v_mov_b32_e32 v82, v2
	v_mov_b32_e32 v83, v2
	v_mov_b32_e32 v84, v2
	v_mov_b32_e32 v85, v2
	v_mov_b32_e32 v90, v2
	v_mov_b32_e32 v91, v2
	v_mov_b32_e32 v92, v2
	v_mov_b32_e32 v93, v2
	v_mov_b32_e32 v98, v2
	v_mov_b32_e32 v99, v2
	v_mov_b32_e32 v100, v2
	v_mov_b32_e32 v101, v2
	v_mov_b32_e32 v106, v2
	v_mov_b32_e32 v107, v2
	v_mov_b32_e32 v108, v2
	v_mov_b32_e32 v109, v2
	v_mov_b32_e32 v114, v2
	v_mov_b32_e32 v115, v2
	v_mov_b32_e32 v116, v2
	v_mov_b32_e32 v117, v2
	v_mov_b32_e32 v122, v2
	v_mov_b32_e32 v123, v2
	v_mov_b32_e32 v124, v2
	v_mov_b32_e32 v125, v2
	v_mov_b32_e32 v70, v2
	v_mov_b32_e32 v71, v2
	v_mov_b32_e32 v72, v2
	v_mov_b32_e32 v73, v2
	v_mov_b32_e32 v78, v2
	v_mov_b32_e32 v79, v2
	v_mov_b32_e32 v80, v2
	v_mov_b32_e32 v81, v2
	v_mov_b32_e32 v86, v2
	v_mov_b32_e32 v87, v2
	v_mov_b32_e32 v88, v2
	v_mov_b32_e32 v89, v2
	v_mov_b32_e32 v94, v2
	v_mov_b32_e32 v95, v2
	v_mov_b32_e32 v96, v2
	v_mov_b32_e32 v97, v2
	v_mov_b32_e32 v102, v2
	v_mov_b32_e32 v103, v2
	v_mov_b32_e32 v104, v2
	v_mov_b32_e32 v105, v2
	v_mov_b32_e32 v110, v2
	v_mov_b32_e32 v111, v2
	v_mov_b32_e32 v112, v2
	v_mov_b32_e32 v113, v2
	v_mov_b32_e32 v118, v2
	v_mov_b32_e32 v119, v2
	v_mov_b32_e32 v120, v2
	v_mov_b32_e32 v121, v2
	v_mov_b32_e32 v126, v2
	v_mov_b32_e32 v127, v2
	v_mov_b32_e32 v128, v2
	v_mov_b32_e32 v129, v2
	v_mov_b32_e32 v62, v2
	v_mov_b32_e32 v63, v2
	v_mov_b32_e32 v64, v2
	v_mov_b32_e32 v65, v2
	v_mov_b32_e32 v54, v2
	v_mov_b32_e32 v55, v2
	v_mov_b32_e32 v56, v2
	v_mov_b32_e32 v57, v2
	v_mov_b32_e32 v46, v2
	v_mov_b32_e32 v47, v2
	v_mov_b32_e32 v48, v2
	v_mov_b32_e32 v49, v2
	v_mov_b32_e32 v38, v2
	v_mov_b32_e32 v39, v2
	v_mov_b32_e32 v40, v2
	v_mov_b32_e32 v41, v2
	v_mov_b32_e32 v30, v2
	v_mov_b32_e32 v31, v2
	v_mov_b32_e32 v32, v2
	v_mov_b32_e32 v33, v2
	v_mov_b32_e32 v22, v2
	v_mov_b32_e32 v23, v2
	v_mov_b32_e32 v24, v2
	v_mov_b32_e32 v25, v2
	v_mov_b32_e32 v10, v2
	v_mov_b32_e32 v11, v2
	v_mov_b32_e32 v12, v2
	v_mov_b32_e32 v13, v2
	v_mov_b32_e32 v18, v2
	v_mov_b32_e32 v19, v2
	v_mov_b32_e32 v20, v2
	v_mov_b32_e32 v21, v2
	s_waitcnt vmcnt(0) lgkmcnt(0)
	s_barrier
	s_branch .LBB0_701

; DI void vm_wait0() { asm volatile("s_waitcnt vmcnt(0)" ::: "memory"); }
;   DI unsigned rowoff(int m) const { int combo = m >> 9, n = m & 511, b = combo >> 1, g = combo & 1; return (unsigned)((b * SEQ + 16 * n) * EIN + col0 + g * 64); }
;   DI unsigned koff(int k) const { return (unsigned)((k >> 6) * EIN + (k & 63)); }
; DI void dma16(const void* g, unsigned char* l) { __builtin_amdgcn_global_load_lds((const unsigned*)g, (lds_u32_t*)(unsigned)(size_t)l, 16, 0, 0); }
; template <class AF, class EF>
; DI void gemm_run(unsigned char* lds, int wv, const AF& af, const bf16_t* __restrict__ Bt, int ldb, int M, int N, int K, const EF& ef, int blk_off) {
;     ...
;   for (int tile_ = first; tile_ < ntl_eff; tile_ += tstep) {
;     int nt, mt;
;     if (xmap) { nt = tile_ % ntiles; mt = (tile_ / ntiles) * 8 + ((int)blockIdx.x & 7); }
;     else { nt = tile_ % ntiles; mt = tile_ / ntiles; }
;     const int m0 = mt << 8, n0 = nt << 8;
;     f32x4 acc[4][8];
; #pragma unroll
;     for (int i = 0; i < 4; ++i)
; #pragma unroll
;       for (int j = 0; j < 8; ++j) acc[i][j] = (f32x4){0.f, 0.f, 0.f, 0.f};
;     unsigned aoff[4], boff[4];
;     const bf16_t* Ab = af.base();
; #pragma unroll
;     for (int i = 0; i < 4; ++i) {
;       int row = crow + 64 * i;
;       aoff[i] = af.rowoff(m0 + row);
;       int n = n0 + row; n = n < N ? n : N - 1;
;       boff[i] = (unsigned)(n * ldb + cch);
;     }
;     __syncthreads();
; #pragma unroll
;     for (int i = 0; i < 4; ++i) {
;       dma16(Ab + aoff[i] + af.koff(cch), sBase + 32768 + (i * 512 + tid) * 16);
;       dma16(Bt + boff[i], sBase + (i * 512 + tid) * 16);
;     }
;     vm_wait0();
;     __syncthreads();
.LBB0_1199:
	s_lshl_b32 s2, s19, 3
	s_or_b32 s2, s2, s78
	s_and_b64 s[8:9], s[6:7], exec
	s_cselect_b32 s2, s2, s19
	s_lshl_b32 s21, s2, 8
	v_add_lshl_u32 v0, s21, v163, 10
	v_readfirstlane_b32 s2, v172
	v_lshl_add_u64 v[8:9], v[0:1], 1, v[138:139]
	s_mov_b32 m0, s2
	v_readfirstlane_b32 s2, v173
	v_add_lshl_u32 v2, s21, v169, 10
	s_barrier
	global_load_lds_dwordx4 v[8:9], off
	s_mov_b32 m0, s2
	v_mov_b32_e32 v3, v1
	v_readfirstlane_b32 s2, v174
	global_load_lds_dwordx4 v[140:141], off
	v_lshl_add_u64 v[2:3], v[2:3], 1, v[138:139]
	s_mov_b32 m0, s2
	v_readfirstlane_b32 s2, v175
	v_add_lshl_u32 v4, s21, v170, 10
	global_load_lds_dwordx4 v[2:3], off
	s_mov_b32 m0, s2
	v_mov_b32_e32 v5, v1
	v_readfirstlane_b32 s2, v176
	global_load_lds_dwordx4 v[142:143], off
	v_lshl_add_u64 v[4:5], v[4:5], 1, v[138:139]
	s_mov_b32 m0, s2
	v_readfirstlane_b32 s2, v177
	v_add_lshl_u32 v6, s21, v171, 10
	global_load_lds_dwordx4 v[4:5], off
	s_mov_b32 m0, s2
	v_mov_b32_e32 v7, v1
	v_readfirstlane_b32 s2, v178
	global_load_lds_dwordx4 v[144:145], off
	v_lshl_add_u64 v[6:7], v[6:7], 1, v[138:139]
	s_mov_b32 m0, s2
	v_readfirstlane_b32 s2, v179
	global_load_lds_dwordx4 v[6:7], off
	s_mov_b32 m0, s2
	v_lshl_add_u64 v[160:161], v[2:3], 0, s[92:93]
	global_load_lds_dwordx4 v[146:147], off
	v_mov_b32_e32 v2, 0
	v_lshl_add_u64 v[158:159], v[8:9], 0, s[92:93]
	v_lshl_add_u64 v[164:165], v[4:5], 0, s[92:93]
	v_lshl_add_u64 v[166:167], v[6:7], 0, s[92:93]
	s_mov_b32 s22, 0
	s_mov_b64 s[8:9], 0
	s_mov_b64 s[10:11], -1
	v_mov_b32_e32 v3, v2
	v_mov_b32_e32 v4, v2
	v_mov_b32_e32 v5, v2
	v_mov_b32_e32 v6, v2
	v_mov_b32_e32 v7, v2
	v_mov_b32_e32 v8, v2
	v_mov_b32_e32 v9, v2
	v_mov_b32_e32 v10, v2
	v_mov_b32_e32 v11, v2
	v_mov_b32_e32 v12, v2
	v_mov_b32_e32 v13, v2
	v_mov_b32_e32 v14, v2
	v_mov_b32_e32 v15, v2
	v_mov_b32_e32 v16, v2
	v_mov_b32_e32 v17, v2
	v_mov_b32_e32 v18, v2
	v_mov_b32_e32 v19, v2
	v_mov_b32_e32 v20, v2
	v_mov_b32_e32 v21, v2
	v_mov_b32_e32 v22, v2
	v_mov_b32_e32 v23, v2
	v_mov_b32_e32 v24, v2
	v_mov_b32_e32 v25, v2
	v_mov_b32_e32 v34, v2
	v_mov_b32_e32 v35, v2
	v_mov_b32_e32 v36, v2
	v_mov_b32_e32 v37, v2
	v_mov_b32_e32 v42, v2
	v_mov_b32_e32 v43, v2
	v_mov_b32_e32 v44, v2
	v_mov_b32_e32 v45, v2
	v_mov_b32_e32 v58, v2
	v_mov_b32_e32 v59, v2
	v_mov_b32_e32 v60, v2
	v_mov_b32_e32 v61, v2
	v_mov_b32_e32 v74, v2
	v_mov_b32_e32 v75, v2
	v_mov_b32_e32 v76, v2
	v_mov_b32_e32 v77, v2
	v_mov_b32_e32 v82, v2
	v_mov_b32_e32 v83, v2
	v_mov_b32_e32 v84, v2
	v_mov_b32_e32 v85, v2
	v_mov_b32_e32 v90, v2
	v_mov_b32_e32 v91, v2
	v_mov_b32_e32 v92, v2
	v_mov_b32_e32 v93, v2
	v_mov_b32_e32 v98, v2
	v_mov_b32_e32 v99, v2
	v_mov_b32_e32 v100, v2
	v_mov_b32_e32 v101, v2
	v_mov_b32_e32 v106, v2
	v_mov_b32_e32 v107, v2
	v_mov_b32_e32 v108, v2
	v_mov_b32_e32 v109, v2
	v_mov_b32_e32 v114, v2
	v_mov_b32_e32 v115, v2
	v_mov_b32_e32 v116, v2
	v_mov_b32_e32 v117, v2
	v_mov_b32_e32 v122, v2
	v_mov_b32_e32 v123, v2
	v_mov_b32_e32 v124, v2
	v_mov_b32_e32 v125, v2
	v_mov_b32_e32 v70, v2
	v_mov_b32_e32 v71, v2
	v_mov_b32_e32 v72, v2
	v_mov_b32_e32 v73, v2
	v_mov_b32_e32 v78, v2
	v_mov_b32_e32 v79, v2
	v_mov_b32_e32 v80, v2
	v_mov_b32_e32 v81, v2
	v_mov_b32_e32 v86, v2
	v_mov_b32_e32 v87, v2
	v_mov_b32_e32 v88, v2
	v_mov_b32_e32 v89, v2
	v_mov_b32_e32 v94, v2
	v_mov_b32_e32 v95, v2
	v_mov_b32_e32 v96, v2
	v_mov_b32_e32 v97, v2
	v_mov_b32_e32 v102, v2
	v_mov_b32_e32 v103, v2
	v_mov_b32_e32 v104, v2
	v_mov_b32_e32 v105, v2
	v_mov_b32_e32 v110, v2
	v_mov_b32_e32 v111, v2
	v_mov_b32_e32 v112, v2
	v_mov_b32_e32 v113, v2
	v_mov_b32_e32 v118, v2
	v_mov_b32_e32 v119, v2
	v_mov_b32_e32 v120, v2
	v_mov_b32_e32 v121, v2
	v_mov_b32_e32 v126, v2
	v_mov_b32_e32 v127, v2
	v_mov_b32_e32 v128, v2
	v_mov_b32_e32 v129, v2
	v_mov_b32_e32 v66, v2
	v_mov_b32_e32 v67, v2
	v_mov_b32_e32 v68, v2
	v_mov_b32_e32 v69, v2
	v_mov_b32_e32 v62, v2
	v_mov_b32_e32 v63, v2
	v_mov_b32_e32 v64, v2
	v_mov_b32_e32 v65, v2
	v_mov_b32_e32 v50, v2
	v_mov_b32_e32 v51, v2
	v_mov_b32_e32 v52, v2
	v_mov_b32_e32 v53, v2
	v_mov_b32_e32 v38, v2
	v_mov_b32_e32 v39, v2
	v_mov_b32_e32 v40, v2
	v_mov_b32_e32 v41, v2
	v_mov_b32_e32 v30, v2
	v_mov_b32_e32 v31, v2
	v_mov_b32_e32 v32, v2
	v_mov_b32_e32 v33, v2
	v_mov_b32_e32 v26, v2
	v_mov_b32_e32 v27, v2
	v_mov_b32_e32 v28, v2
	v_mov_b32_e32 v29, v2
	v_mov_b32_e32 v54, v2
	v_mov_b32_e32 v55, v2
	v_mov_b32_e32 v56, v2
	v_mov_b32_e32 v57, v2
	v_mov_b32_e32 v46, v2
	v_mov_b32_e32 v47, v2
	v_mov_b32_e32 v48, v2
	v_mov_b32_e32 v49, v2
	s_waitcnt vmcnt(0) lgkmcnt(0)
	s_barrier
	s_branch .LBB0_1201

; DI void vm_wait0() { asm volatile("s_waitcnt vmcnt(0)" ::: "memory"); }
;   DI unsigned rowoff(int m) const { int combo = m >> 9, n = m & 511, b = combo >> 1, g = combo & 1; return (unsigned)((b * SEQ + 16 * n) * EIN + col0 + g * 64); }
;   DI unsigned koff(int k) const { return (unsigned)((k >> 6) * EIN + (k & 63)); }
; DI void dma16(const void* g, unsigned char* l) { __builtin_amdgcn_global_load_lds((const unsigned*)g, (lds_u32_t*)(unsigned)(size_t)l, 16, 0, 0); }
; template <class AF, class EF>
; DI void gemm_run(unsigned char* lds, int wv, const AF& af, const bf16_t* __restrict__ Bt, int ldb, int M, int N, int K, const EF& ef, int blk_off) {
;     ...
;   for (int tile_ = first; tile_ < ntl_eff; tile_ += tstep) {
;     int nt, mt;
;     if (xmap) { nt = tile_ % ntiles; mt = (tile_ / ntiles) * 8 + ((int)blockIdx.x & 7); }
;     else { nt = tile_ % ntiles; mt = tile_ / ntiles; }
;     const int m0 = mt << 8, n0 = nt << 8;
;     f32x4 acc[4][8];
; #pragma unroll
;     for (int i = 0; i < 4; ++i)
; #pragma unroll
;       for (int j = 0; j < 8; ++j) acc[i][j] = (f32x4){0.f, 0.f, 0.f, 0.f};
;     unsigned aoff[4], boff[4];
;     const bf16_t* Ab = af.base();
; #pragma unroll
;     for (int i = 0; i < 4; ++i) {
;       int row = crow + 64 * i;
;       aoff[i] = af.rowoff(m0 + row);
;       int n = n0 + row; n = n < N ? n : N - 1;
;       boff[i] = (unsigned)(n * ldb + cch);
;     }
;     __syncthreads();
; #pragma unroll
;     for (int i = 0; i < 4; ++i) {
;       dma16(Ab + aoff[i] + af.koff(cch), sBase + 32768 + (i * 512 + tid) * 16);
;       dma16(Bt + boff[i], sBase + (i * 512 + tid) * 16);
;     }
;     vm_wait0();
;     __syncthreads();
.LBB0_1244:
	s_ashr_i32 s14, s16, 31
	s_lshr_b32 s14, s14, 30
	s_add_i32 s18, s16, s14
	s_ashr_i32 s17, s18, 2
	s_lshl_b32 s14, s17, 3
	s_or_b32 s19, s14, s78
	v_readlane_b32 s14, v254, 34
	v_readlane_b32 s15, v254, 35
	s_and_b64 s[14:15], s[14:15], exec
	s_cselect_b32 s14, s19, s17
	s_lshl_b32 s17, s14, 8
	s_and_b32 s14, s18, 0xfffffc
	s_sub_i32 s14, s16, s14
	s_lshl_b32 s18, s14, 8
	v_add_u32_e32 v3, s18, v168
	v_min_i32_e32 v3, 0x3ff, v3
	v_lshl_or_b32 v6, v3, 10, v145
	v_add_u32_e32 v3, s18, v169
	v_min_i32_e32 v3, 0x3ff, v3
	v_add_u32_e32 v2, s18, v143
	v_lshl_or_b32 v10, v3, 10, v145
	v_add_u32_e32 v3, s18, v170
	v_add_lshl_u32 v0, s17, v143, 10
	v_min_i32_e32 v2, 0x3ff, v2
	v_min_i32_e32 v3, 0x3ff, v3
	v_lshl_or_b32 v2, v2, 10, v145
	v_lshl_or_b32 v14, v3, 10, v145
	v_lshlrev_b64 v[16:17], 1, v[0:1]
	v_readfirstlane_b32 s14, v171
	v_mov_b32_e32 v3, v1
	v_add_lshl_u32 v4, s17, v168, 10
	v_lshl_add_u64 v[18:19], v[138:139], 0, v[16:17]
	s_mov_b32 m0, s14
	v_lshlrev_b64 v[2:3], 1, v[2:3]
	v_readfirstlane_b32 s14, v172
	v_mov_b32_e32 v5, v1
	s_waitcnt lgkmcnt(0)
	s_barrier
	global_load_lds_dwordx4 v[18:19], off
	v_lshl_add_u64 v[18:19], s[4:5], 0, v[2:3]
	s_mov_b32 m0, s14
	v_lshlrev_b64 v[4:5], 1, v[4:5]
	v_readfirstlane_b32 s14, v173
	v_mov_b32_e32 v7, v1
	v_add_lshl_u32 v8, s17, v169, 10
	global_load_lds_dwordx4 v[18:19], off
	v_lshl_add_u64 v[18:19], v[138:139], 0, v[4:5]
	s_mov_b32 m0, s14
	v_lshlrev_b64 v[6:7], 1, v[6:7]
	v_readfirstlane_b32 s14, v174
	v_mov_b32_e32 v9, v1
	global_load_lds_dwordx4 v[18:19], off
	v_lshl_add_u64 v[18:19], s[4:5], 0, v[6:7]
	s_mov_b32 m0, s14
	v_lshlrev_b64 v[8:9], 1, v[8:9]
	v_readfirstlane_b32 s14, v175
	v_mov_b32_e32 v11, v1
	v_add_lshl_u32 v12, s17, v170, 10
	global_load_lds_dwordx4 v[18:19], off
	v_lshl_add_u64 v[18:19], v[138:139], 0, v[8:9]
	s_mov_b32 m0, s14
	v_lshlrev_b64 v[10:11], 1, v[10:11]
	v_readfirstlane_b32 s14, v176
	v_mov_b32_e32 v13, v1
	global_load_lds_dwordx4 v[18:19], off
	v_lshl_add_u64 v[18:19], s[4:5], 0, v[10:11]
	s_mov_b32 m0, s14
	v_lshlrev_b64 v[12:13], 1, v[12:13]
	v_readfirstlane_b32 s14, v177
	v_mov_b32_e32 v15, v1
	global_load_lds_dwordx4 v[18:19], off
	v_lshl_add_u64 v[18:19], v[138:139], 0, v[12:13]
	s_mov_b32 m0, s14
	v_lshlrev_b64 v[14:15], 1, v[14:15]
	v_readfirstlane_b32 s14, v178
	global_load_lds_dwordx4 v[18:19], off
	v_lshl_add_u64 v[18:19], s[4:5], 0, v[14:15]
	s_mov_b32 m0, s14
	v_lshl_add_u64 v[156:157], s[12:13], 0, v[2:3]
	global_load_lds_dwordx4 v[18:19], off
	v_mov_b32_e32 v2, 0
	v_lshl_add_u64 v[150:151], s[12:13], 0, v[14:15]
	v_lshl_add_u64 v[152:153], s[12:13], 0, v[10:11]
	v_lshl_add_u64 v[154:155], s[12:13], 0, v[6:7]
	v_lshl_add_u64 v[158:159], v[148:149], 0, v[12:13]
	v_lshl_add_u64 v[160:161], v[148:149], 0, v[8:9]
	v_lshl_add_u64 v[164:165], v[148:149], 0, v[4:5]
	v_lshl_add_u64 v[166:167], v[148:149], 0, v[16:17]
	s_mov_b32 s19, 0
	s_mov_b64 s[14:15], 0
	s_mov_b32 s20, 0x10000
	v_mov_b32_e32 v3, v2
	v_mov_b32_e32 v4, v2
	v_mov_b32_e32 v5, v2
	v_mov_b32_e32 v6, v2
	v_mov_b32_e32 v7, v2
	v_mov_b32_e32 v8, v2
	v_mov_b32_e32 v9, v2
	v_mov_b32_e32 v10, v2
	v_mov_b32_e32 v11, v2
	v_mov_b32_e32 v12, v2
	v_mov_b32_e32 v13, v2
	v_mov_b32_e32 v14, v2
	v_mov_b32_e32 v15, v2
	v_mov_b32_e32 v16, v2
	v_mov_b32_e32 v17, v2
	v_mov_b32_e32 v30, v2
	v_mov_b32_e32 v31, v2
	v_mov_b32_e32 v32, v2
	v_mov_b32_e32 v33, v2
	v_mov_b32_e32 v42, v2
	v_mov_b32_e32 v43, v2
	v_mov_b32_e32 v44, v2
	v_mov_b32_e32 v45, v2
	v_mov_b32_e32 v50, v2
	v_mov_b32_e32 v51, v2
	v_mov_b32_e32 v52, v2
	v_mov_b32_e32 v53, v2
	v_mov_b32_e32 v58, v2
	v_mov_b32_e32 v59, v2
	v_mov_b32_e32 v60, v2
	v_mov_b32_e32 v61, v2
	v_mov_b32_e32 v66, v2
	v_mov_b32_e32 v67, v2
	v_mov_b32_e32 v68, v2
	v_mov_b32_e32 v69, v2
	v_mov_b32_e32 v74, v2
	v_mov_b32_e32 v75, v2
	v_mov_b32_e32 v76, v2
	v_mov_b32_e32 v77, v2
	v_mov_b32_e32 v82, v2
	v_mov_b32_e32 v83, v2
	v_mov_b32_e32 v84, v2
	v_mov_b32_e32 v85, v2
	v_mov_b32_e32 v90, v2
	v_mov_b32_e32 v91, v2
	v_mov_b32_e32 v92, v2
	v_mov_b32_e32 v93, v2
	v_mov_b32_e32 v98, v2
	v_mov_b32_e32 v99, v2
	v_mov_b32_e32 v100, v2
	v_mov_b32_e32 v101, v2
	v_mov_b32_e32 v106, v2
	v_mov_b32_e32 v107, v2
	v_mov_b32_e32 v108, v2
	v_mov_b32_e32 v109, v2
	v_mov_b32_e32 v114, v2
	v_mov_b32_e32 v115, v2
	v_mov_b32_e32 v116, v2
	v_mov_b32_e32 v117, v2
	v_mov_b32_e32 v122, v2
	v_mov_b32_e32 v123, v2
	v_mov_b32_e32 v124, v2
	v_mov_b32_e32 v125, v2
	v_mov_b32_e32 v70, v2
	v_mov_b32_e32 v71, v2
	v_mov_b32_e32 v72, v2
	v_mov_b32_e32 v73, v2
	v_mov_b32_e32 v78, v2
	v_mov_b32_e32 v79, v2
	v_mov_b32_e32 v80, v2
	v_mov_b32_e32 v81, v2
	v_mov_b32_e32 v86, v2
	v_mov_b32_e32 v87, v2
	v_mov_b32_e32 v88, v2
	v_mov_b32_e32 v89, v2
	v_mov_b32_e32 v94, v2
	v_mov_b32_e32 v95, v2
	v_mov_b32_e32 v96, v2
	v_mov_b32_e32 v97, v2
	v_mov_b32_e32 v102, v2
	v_mov_b32_e32 v103, v2
	v_mov_b32_e32 v104, v2
	v_mov_b32_e32 v105, v2
	v_mov_b32_e32 v110, v2
	v_mov_b32_e32 v111, v2
	v_mov_b32_e32 v112, v2
	v_mov_b32_e32 v113, v2
	v_mov_b32_e32 v118, v2
	v_mov_b32_e32 v119, v2
	v_mov_b32_e32 v120, v2
	v_mov_b32_e32 v121, v2
	v_mov_b32_e32 v126, v2
	v_mov_b32_e32 v127, v2
	v_mov_b32_e32 v128, v2
	v_mov_b32_e32 v129, v2
	v_mov_b32_e32 v62, v2
	v_mov_b32_e32 v63, v2
	v_mov_b32_e32 v64, v2
	v_mov_b32_e32 v65, v2
	v_mov_b32_e32 v54, v2
	v_mov_b32_e32 v55, v2
	v_mov_b32_e32 v56, v2
	v_mov_b32_e32 v57, v2
	v_mov_b32_e32 v46, v2
	v_mov_b32_e32 v47, v2
	v_mov_b32_e32 v48, v2
	v_mov_b32_e32 v49, v2
	v_mov_b32_e32 v38, v2
	v_mov_b32_e32 v39, v2
	v_mov_b32_e32 v40, v2
	v_mov_b32_e32 v41, v2
	v_mov_b32_e32 v26, v2
	v_mov_b32_e32 v27, v2
	v_mov_b32_e32 v28, v2
	v_mov_b32_e32 v29, v2
	v_mov_b32_e32 v22, v2
	v_mov_b32_e32 v23, v2
	v_mov_b32_e32 v24, v2
	v_mov_b32_e32 v25, v2
	v_mov_b32_e32 v34, v2
	v_mov_b32_e32 v35, v2
	v_mov_b32_e32 v36, v2
	v_mov_b32_e32 v37, v2
	v_mov_b32_e32 v18, v2
	v_mov_b32_e32 v19, v2
	v_mov_b32_e32 v20, v2
	v_mov_b32_e32 v21, v2
	s_waitcnt vmcnt(0) lgkmcnt(0)
	s_barrier
	s_branch .LBB0_1246

; DI void vm_wait0() { asm volatile("s_waitcnt vmcnt(0)" ::: "memory"); }
;   DI unsigned rowoff(int m) const { int combo = m >> 9, n = m & 511, b = combo >> 1, g = combo & 1; return (unsigned)((b * SEQ + 16 * n) * EIN + col0 + g * 64); }
;   DI unsigned koff(int k) const { return (unsigned)((k >> 6) * EIN + (k & 63)); }
; DI void dma16(const void* g, unsigned char* l) { __builtin_amdgcn_global_load_lds((const unsigned*)g, (lds_u32_t*)(unsigned)(size_t)l, 16, 0, 0); }
; template <class AF, class EF>
; DI void gemm_run(unsigned char* lds, int wv, const AF& af, const bf16_t* __restrict__ Bt, int ldb, int M, int N, int K, const EF& ef, int blk_off) {
;     ...
;   for (int tile_ = first; tile_ < ntl_eff; tile_ += tstep) {
;     int nt, mt;
;     if (xmap) { nt = tile_ % ntiles; mt = (tile_ / ntiles) * 8 + ((int)blockIdx.x & 7); }
;     else { nt = tile_ % ntiles; mt = tile_ / ntiles; }
;     const int m0 = mt << 8, n0 = nt << 8;
;     f32x4 acc[4][8];
; #pragma unroll
;     for (int i = 0; i < 4; ++i)
; #pragma unroll
;       for (int j = 0; j < 8; ++j) acc[i][j] = (f32x4){0.f, 0.f, 0.f, 0.f};
;     unsigned aoff[4], boff[4];
;     const bf16_t* Ab = af.base();
; #pragma unroll
;     for (int i = 0; i < 4; ++i) {
;       int row = crow + 64 * i;
;       aoff[i] = af.rowoff(m0 + row);
;       int n = n0 + row; n = n < N ? n : N - 1;
;       boff[i] = (unsigned)(n * ldb + cch);
;     }
;     __syncthreads();
; #pragma unroll
;     for (int i = 0; i < 4; ++i) {
;       dma16(Ab + aoff[i] + af.koff(cch), sBase + 32768 + (i * 512 + tid) * 16);
;       dma16(Bt + boff[i], sBase + (i * 512 + tid) * 16);
;     }
;     vm_wait0();
;     __syncthreads();
.LBB0_1266:
	s_ashr_i32 s10, s12, 31
	s_lshr_b32 s10, s10, 28
	s_add_i32 s14, s12, s10
	s_ashr_i32 s13, s14, 4
	s_lshl_b32 s10, s13, 3
	s_or_b32 s15, s10, s78
	v_readlane_b32 s10, v254, 34
	v_readlane_b32 s11, v254, 35
	s_and_b64 s[10:11], s[10:11], exec
	s_cselect_b32 s10, s15, s13
	s_lshl_b32 s13, s10, 8
	s_and_b32 s10, s14, 0xfffff0
	s_sub_i32 s10, s12, s10
	s_lshl_b32 s14, s10, 8
	v_add_u32_e32 v3, s14, v163
	v_min_i32_e32 v3, 0xfff, v3
	v_lshl_or_b32 v6, v3, 10, v139
	v_add_u32_e32 v3, s14, v164
	v_min_i32_e32 v3, 0xfff, v3
	v_add_u32_e32 v2, s14, v137
	v_lshl_or_b32 v10, v3, 10, v139
	v_add_u32_e32 v3, s14, v165
	v_add_lshl_u32 v0, s13, v137, 10
	v_min_i32_e32 v2, 0xfff, v2
	v_min_i32_e32 v3, 0xfff, v3
	v_lshl_or_b32 v2, v2, 10, v139
	v_lshl_or_b32 v14, v3, 10, v139
	v_lshlrev_b64 v[16:17], 1, v[0:1]
	v_readfirstlane_b32 s10, v166
	v_mov_b32_e32 v3, v1
	v_add_lshl_u32 v4, s13, v163, 10
	v_lshl_add_u64 v[18:19], v[134:135], 0, v[16:17]
	s_mov_b32 m0, s10
	v_lshlrev_b64 v[2:3], 1, v[2:3]
	v_readfirstlane_b32 s10, v167
	v_mov_b32_e32 v5, v1
	s_barrier
	global_load_lds_dwordx4 v[18:19], off
	v_lshl_add_u64 v[18:19], s[4:5], 0, v[2:3]
	s_mov_b32 m0, s10
	v_lshlrev_b64 v[4:5], 1, v[4:5]
	v_readfirstlane_b32 s10, v168
	v_mov_b32_e32 v7, v1
	v_add_lshl_u32 v8, s13, v164, 10
	global_load_lds_dwordx4 v[18:19], off
	v_lshl_add_u64 v[18:19], v[134:135], 0, v[4:5]
	s_mov_b32 m0, s10
	v_lshlrev_b64 v[6:7], 1, v[6:7]
	v_readfirstlane_b32 s10, v169
	v_mov_b32_e32 v9, v1
	global_load_lds_dwordx4 v[18:19], off
	v_lshl_add_u64 v[18:19], s[4:5], 0, v[6:7]
	s_mov_b32 m0, s10
	v_lshlrev_b64 v[8:9], 1, v[8:9]
	v_readfirstlane_b32 s10, v170
	v_mov_b32_e32 v11, v1
	v_add_lshl_u32 v12, s13, v165, 10
	global_load_lds_dwordx4 v[18:19], off
	v_lshl_add_u64 v[18:19], v[134:135], 0, v[8:9]
	s_mov_b32 m0, s10
	v_lshlrev_b64 v[10:11], 1, v[10:11]
	v_readfirstlane_b32 s10, v171
	v_mov_b32_e32 v13, v1
	global_load_lds_dwordx4 v[18:19], off
	v_lshl_add_u64 v[18:19], s[4:5], 0, v[10:11]
	s_mov_b32 m0, s10
	v_lshlrev_b64 v[12:13], 1, v[12:13]
	v_readfirstlane_b32 s10, v172
	v_mov_b32_e32 v15, v1
	global_load_lds_dwordx4 v[18:19], off
	v_lshl_add_u64 v[18:19], v[134:135], 0, v[12:13]
	s_mov_b32 m0, s10
	v_lshlrev_b64 v[14:15], 1, v[14:15]
	v_readfirstlane_b32 s10, v173
	global_load_lds_dwordx4 v[18:19], off
	v_lshl_add_u64 v[18:19], s[4:5], 0, v[14:15]
	s_mov_b32 m0, s10
	v_lshl_add_u64 v[152:153], s[8:9], 0, v[2:3]
	global_load_lds_dwordx4 v[18:19], off
	v_mov_b32_e32 v2, 0
	v_lshl_add_u64 v[146:147], s[8:9], 0, v[14:15]
	v_lshl_add_u64 v[148:149], s[8:9], 0, v[10:11]
	v_lshl_add_u64 v[150:151], s[8:9], 0, v[6:7]
	v_lshl_add_u64 v[154:155], v[144:145], 0, v[12:13]
	v_lshl_add_u64 v[156:157], v[144:145], 0, v[8:9]
	v_lshl_add_u64 v[158:159], v[144:145], 0, v[4:5]
	v_lshl_add_u64 v[160:161], v[144:145], 0, v[16:17]
	s_mov_b64 s[10:11], 0
	s_mov_b32 s15, 0x10000
	v_mov_b32_e32 v3, v2
	v_mov_b32_e32 v4, v2
	v_mov_b32_e32 v5, v2
	v_mov_b32_e32 v6, v2
	v_mov_b32_e32 v7, v2
	v_mov_b32_e32 v8, v2
	v_mov_b32_e32 v9, v2
	v_mov_b32_e32 v10, v2
	v_mov_b32_e32 v11, v2
	v_mov_b32_e32 v12, v2
	v_mov_b32_e32 v13, v2
	v_mov_b32_e32 v14, v2
	v_mov_b32_e32 v15, v2
	v_mov_b32_e32 v16, v2
	v_mov_b32_e32 v17, v2
	v_mov_b32_e32 v26, v2
	v_mov_b32_e32 v27, v2
	v_mov_b32_e32 v28, v2
	v_mov_b32_e32 v29, v2
	v_mov_b32_e32 v38, v2
	v_mov_b32_e32 v39, v2
	v_mov_b32_e32 v40, v2
	v_mov_b32_e32 v41, v2
	v_mov_b32_e32 v46, v2
	v_mov_b32_e32 v47, v2
	v_mov_b32_e32 v48, v2
	v_mov_b32_e32 v49, v2
	v_mov_b32_e32 v54, v2
	v_mov_b32_e32 v55, v2
	v_mov_b32_e32 v56, v2
	v_mov_b32_e32 v57, v2
	v_mov_b32_e32 v62, v2
	v_mov_b32_e32 v63, v2
	v_mov_b32_e32 v64, v2
	v_mov_b32_e32 v65, v2
	v_mov_b32_e32 v74, v2
	v_mov_b32_e32 v75, v2
	v_mov_b32_e32 v76, v2
	v_mov_b32_e32 v77, v2
	v_mov_b32_e32 v82, v2
	v_mov_b32_e32 v83, v2
	v_mov_b32_e32 v84, v2
	v_mov_b32_e32 v85, v2
	v_mov_b32_e32 v90, v2
	v_mov_b32_e32 v91, v2
	v_mov_b32_e32 v92, v2
	v_mov_b32_e32 v93, v2
	v_mov_b32_e32 v98, v2
	v_mov_b32_e32 v99, v2
	v_mov_b32_e32 v100, v2
	v_mov_b32_e32 v101, v2
	v_mov_b32_e32 v106, v2
	v_mov_b32_e32 v107, v2
	v_mov_b32_e32 v108, v2
	v_mov_b32_e32 v109, v2
	v_mov_b32_e32 v114, v2
	v_mov_b32_e32 v115, v2
	v_mov_b32_e32 v116, v2
	v_mov_b32_e32 v117, v2
	v_mov_b32_e32 v122, v2
	v_mov_b32_e32 v123, v2
	v_mov_b32_e32 v124, v2
	v_mov_b32_e32 v125, v2
	v_mov_b32_e32 v70, v2
	v_mov_b32_e32 v71, v2
	v_mov_b32_e32 v72, v2
	v_mov_b32_e32 v73, v2
	v_mov_b32_e32 v78, v2
	v_mov_b32_e32 v79, v2
	v_mov_b32_e32 v80, v2
	v_mov_b32_e32 v81, v2
	v_mov_b32_e32 v86, v2
	v_mov_b32_e32 v87, v2
	v_mov_b32_e32 v88, v2
	v_mov_b32_e32 v89, v2
	v_mov_b32_e32 v94, v2
	v_mov_b32_e32 v95, v2
	v_mov_b32_e32 v96, v2
	v_mov_b32_e32 v97, v2
	v_mov_b32_e32 v102, v2
	v_mov_b32_e32 v103, v2
	v_mov_b32_e32 v104, v2
	v_mov_b32_e32 v105, v2
	v_mov_b32_e32 v110, v2
	v_mov_b32_e32 v111, v2
	v_mov_b32_e32 v112, v2
	v_mov_b32_e32 v113, v2
	v_mov_b32_e32 v118, v2
	v_mov_b32_e32 v119, v2
	v_mov_b32_e32 v120, v2
	v_mov_b32_e32 v121, v2
	v_mov_b32_e32 v126, v2
	v_mov_b32_e32 v127, v2
	v_mov_b32_e32 v128, v2
	v_mov_b32_e32 v129, v2
	v_mov_b32_e32 v66, v2
	v_mov_b32_e32 v67, v2
	v_mov_b32_e32 v68, v2
	v_mov_b32_e32 v69, v2
	v_mov_b32_e32 v58, v2
	v_mov_b32_e32 v59, v2
	v_mov_b32_e32 v60, v2
	v_mov_b32_e32 v61, v2
	v_mov_b32_e32 v50, v2
	v_mov_b32_e32 v51, v2
	v_mov_b32_e32 v52, v2
	v_mov_b32_e32 v53, v2
	v_mov_b32_e32 v42, v2
	v_mov_b32_e32 v43, v2
	v_mov_b32_e32 v44, v2
	v_mov_b32_e32 v45, v2
	v_mov_b32_e32 v30, v2
	v_mov_b32_e32 v31, v2
	v_mov_b32_e32 v32, v2
	v_mov_b32_e32 v33, v2
	v_mov_b32_e32 v22, v2
	v_mov_b32_e32 v23, v2
	v_mov_b32_e32 v24, v2
	v_mov_b32_e32 v25, v2
	v_mov_b32_e32 v18, v2
	v_mov_b32_e32 v19, v2
	v_mov_b32_e32 v20, v2
	v_mov_b32_e32 v21, v2
	v_mov_b32_e32 v34, v2
	v_mov_b32_e32 v35, v2
	v_mov_b32_e32 v36, v2
	v_mov_b32_e32 v37, v2
	s_waitcnt vmcnt(0) lgkmcnt(0)
	s_barrier
	s_branch .LBB0_1268

; DI void vm_wait0() { asm volatile("s_waitcnt vmcnt(0)" ::: "memory"); }
;   DI unsigned rowoff(int m) const { int combo = m >> 9, n = m & 511, b = combo >> 1, g = combo & 1; return (unsigned)((b * SEQ + 16 * n) * EIN + col0 + g * 64); }
;   DI unsigned koff(int k) const { return (unsigned)((k >> 6) * EIN + (k & 63)); }
; DI void dma16(const void* g, unsigned char* l) { __builtin_amdgcn_global_load_lds((const unsigned*)g, (lds_u32_t*)(unsigned)(size_t)l, 16, 0, 0); }
; template <class AF, class EF>
; DI void gemm_run(unsigned char* lds, int wv, const AF& af, const bf16_t* __restrict__ Bt, int ldb, int M, int N, int K, const EF& ef, int blk_off) {
;     ...
;   for (int tile_ = first; tile_ < ntl_eff; tile_ += tstep) {
;     int nt, mt;
;     if (xmap) { nt = tile_ % ntiles; mt = (tile_ / ntiles) * 8 + ((int)blockIdx.x & 7); }
;     else { nt = tile_ % ntiles; mt = tile_ / ntiles; }
;     const int m0 = mt << 8, n0 = nt << 8;
;     f32x4 acc[4][8];
; #pragma unroll
;     for (int i = 0; i < 4; ++i)
; #pragma unroll
;       for (int j = 0; j < 8; ++j) acc[i][j] = (f32x4){0.f, 0.f, 0.f, 0.f};
;     unsigned aoff[4], boff[4];
;     const bf16_t* Ab = af.base();
; #pragma unroll
;     for (int i = 0; i < 4; ++i) {
;       int row = crow + 64 * i;
;       aoff[i] = af.rowoff(m0 + row);
;       int n = n0 + row; n = n < N ? n : N - 1;
;       boff[i] = (unsigned)(n * ldb + cch);
;     }
;     __syncthreads();
; #pragma unroll
;     for (int i = 0; i < 4; ++i) {
;       dma16(Ab + aoff[i] + af.koff(cch), sBase + 32768 + (i * 512 + tid) * 16);
;       dma16(Bt + boff[i], sBase + (i * 512 + tid) * 16);
;     }
;     vm_wait0();
;     __syncthreads();
.LBB0_1278:
	s_ashr_i32 s16, s18, 31
	s_lshr_b32 s16, s16, 30
	s_add_i32 s20, s18, s16
	s_ashr_i32 s19, s20, 2
	s_lshl_b32 s16, s19, 3
	s_or_b32 s21, s16, s78
	v_readlane_b32 s16, v254, 34
	v_readlane_b32 s17, v254, 35
	s_and_b64 s[16:17], s[16:17], exec
	s_cselect_b32 s16, s21, s19
	s_lshl_b32 s19, s16, 8
	s_and_b32 s16, s20, 0xfffffc
	s_sub_i32 s16, s18, s16
	s_lshl_b32 s20, s16, 8
	v_add_u32_e32 v3, s20, v168
	v_min_i32_e32 v3, 0x3ff, v3
	v_lshl_or_b32 v6, v3, 12, v145
	v_add_u32_e32 v3, s20, v169
	v_min_i32_e32 v3, 0x3ff, v3
	v_add_u32_e32 v2, s20, v143
	v_lshl_or_b32 v10, v3, 12, v145
	v_add_u32_e32 v3, s20, v170
	v_add_lshl_u32 v0, s19, v143, 12
	v_min_i32_e32 v2, 0x3ff, v2
	v_min_i32_e32 v3, 0x3ff, v3
	v_lshl_or_b32 v2, v2, 12, v145
	v_lshl_or_b32 v14, v3, 12, v145
	v_lshlrev_b64 v[16:17], 1, v[0:1]
	v_readfirstlane_b32 s16, v171
	v_mov_b32_e32 v3, v1
	v_add_lshl_u32 v4, s19, v168, 12
	v_lshl_add_u64 v[18:19], v[138:139], 0, v[16:17]
	s_mov_b32 m0, s16
	v_lshlrev_b64 v[2:3], 1, v[2:3]
	v_readfirstlane_b32 s16, v172
	v_mov_b32_e32 v5, v1
	s_waitcnt lgkmcnt(0)
	s_barrier
	global_load_lds_dwordx4 v[18:19], off
	v_lshl_add_u64 v[18:19], s[4:5], 0, v[2:3]
	s_mov_b32 m0, s16
	v_lshlrev_b64 v[4:5], 1, v[4:5]
	v_readfirstlane_b32 s16, v173
	v_mov_b32_e32 v7, v1
	v_add_lshl_u32 v8, s19, v169, 12
	global_load_lds_dwordx4 v[18:19], off
	v_lshl_add_u64 v[18:19], v[138:139], 0, v[4:5]
	s_mov_b32 m0, s16
	v_lshlrev_b64 v[6:7], 1, v[6:7]
	v_readfirstlane_b32 s16, v174
	v_mov_b32_e32 v9, v1
	global_load_lds_dwordx4 v[18:19], off
	v_lshl_add_u64 v[18:19], s[4:5], 0, v[6:7]
	s_mov_b32 m0, s16
	v_lshlrev_b64 v[8:9], 1, v[8:9]
	v_readfirstlane_b32 s16, v175
	v_mov_b32_e32 v11, v1
	v_add_lshl_u32 v12, s19, v170, 12
	global_load_lds_dwordx4 v[18:19], off
	v_lshl_add_u64 v[18:19], v[138:139], 0, v[8:9]
	s_mov_b32 m0, s16
	v_lshlrev_b64 v[10:11], 1, v[10:11]
	v_readfirstlane_b32 s16, v176
	v_mov_b32_e32 v13, v1
	global_load_lds_dwordx4 v[18:19], off
	v_lshl_add_u64 v[18:19], s[4:5], 0, v[10:11]
	s_mov_b32 m0, s16
	v_lshlrev_b64 v[12:13], 1, v[12:13]
	v_readfirstlane_b32 s16, v177
	v_mov_b32_e32 v15, v1
	global_load_lds_dwordx4 v[18:19], off
	v_lshl_add_u64 v[18:19], v[138:139], 0, v[12:13]
	s_mov_b32 m0, s16
	v_lshlrev_b64 v[14:15], 1, v[14:15]
	v_readfirstlane_b32 s16, v178
	global_load_lds_dwordx4 v[18:19], off
	v_lshl_add_u64 v[18:19], s[4:5], 0, v[14:15]
	s_mov_b32 m0, s16
	v_lshl_add_u64 v[156:157], s[14:15], 0, v[2:3]
	global_load_lds_dwordx4 v[18:19], off
	v_mov_b32_e32 v2, 0
	v_lshl_add_u64 v[150:151], s[14:15], 0, v[14:15]
	v_lshl_add_u64 v[152:153], s[14:15], 0, v[10:11]
	v_lshl_add_u64 v[154:155], s[14:15], 0, v[6:7]
	v_lshl_add_u64 v[158:159], v[148:149], 0, v[12:13]
	v_lshl_add_u64 v[160:161], v[148:149], 0, v[8:9]
	v_lshl_add_u64 v[164:165], v[148:149], 0, v[4:5]
	v_lshl_add_u64 v[166:167], v[148:149], 0, v[16:17]
	s_mov_b32 s21, 0
	s_mov_b64 s[16:17], 0
	s_mov_b32 s22, 0x10000
	v_mov_b32_e32 v3, v2
	v_mov_b32_e32 v4, v2
	v_mov_b32_e32 v5, v2
	v_mov_b32_e32 v6, v2
	v_mov_b32_e32 v7, v2
	v_mov_b32_e32 v8, v2
	v_mov_b32_e32 v9, v2
	v_mov_b32_e32 v10, v2
	v_mov_b32_e32 v11, v2
	v_mov_b32_e32 v12, v2
	v_mov_b32_e32 v13, v2
	v_mov_b32_e32 v14, v2
	v_mov_b32_e32 v15, v2
	v_mov_b32_e32 v16, v2
	v_mov_b32_e32 v17, v2
	v_mov_b32_e32 v30, v2
	v_mov_b32_e32 v31, v2
	v_mov_b32_e32 v32, v2
	v_mov_b32_e32 v33, v2
	v_mov_b32_e32 v42, v2
	v_mov_b32_e32 v43, v2
	v_mov_b32_e32 v44, v2
	v_mov_b32_e32 v45, v2
	v_mov_b32_e32 v50, v2
	v_mov_b32_e32 v51, v2
	v_mov_b32_e32 v52, v2
	v_mov_b32_e32 v53, v2
	v_mov_b32_e32 v58, v2
	v_mov_b32_e32 v59, v2
	v_mov_b32_e32 v60, v2
	v_mov_b32_e32 v61, v2
	v_mov_b32_e32 v66, v2
	v_mov_b32_e32 v67, v2
	v_mov_b32_e32 v68, v2
	v_mov_b32_e32 v69, v2
	v_mov_b32_e32 v74, v2
	v_mov_b32_e32 v75, v2
	v_mov_b32_e32 v76, v2
	v_mov_b32_e32 v77, v2
	v_mov_b32_e32 v82, v2
	v_mov_b32_e32 v83, v2
	v_mov_b32_e32 v84, v2
	v_mov_b32_e32 v85, v2
	v_mov_b32_e32 v90, v2
	v_mov_b32_e32 v91, v2
	v_mov_b32_e32 v92, v2
	v_mov_b32_e32 v93, v2
	v_mov_b32_e32 v98, v2
	v_mov_b32_e32 v99, v2
	v_mov_b32_e32 v100, v2
	v_mov_b32_e32 v101, v2
	v_mov_b32_e32 v106, v2
	v_mov_b32_e32 v107, v2
	v_mov_b32_e32 v108, v2
	v_mov_b32_e32 v109, v2
	v_mov_b32_e32 v114, v2
	v_mov_b32_e32 v115, v2
	v_mov_b32_e32 v116, v2
	v_mov_b32_e32 v117, v2
	v_mov_b32_e32 v122, v2
	v_mov_b32_e32 v123, v2
	v_mov_b32_e32 v124, v2
	v_mov_b32_e32 v125, v2
	v_mov_b32_e32 v70, v2
	v_mov_b32_e32 v71, v2
	v_mov_b32_e32 v72, v2
	v_mov_b32_e32 v73, v2
	v_mov_b32_e32 v78, v2
	v_mov_b32_e32 v79, v2
	v_mov_b32_e32 v80, v2
	v_mov_b32_e32 v81, v2
	v_mov_b32_e32 v86, v2
	v_mov_b32_e32 v87, v2
	v_mov_b32_e32 v88, v2
	v_mov_b32_e32 v89, v2
	v_mov_b32_e32 v94, v2
	v_mov_b32_e32 v95, v2
	v_mov_b32_e32 v96, v2
	v_mov_b32_e32 v97, v2
	v_mov_b32_e32 v102, v2
	v_mov_b32_e32 v103, v2
	v_mov_b32_e32 v104, v2
	v_mov_b32_e32 v105, v2
	v_mov_b32_e32 v110, v2
	v_mov_b32_e32 v111, v2
	v_mov_b32_e32 v112, v2
	v_mov_b32_e32 v113, v2
	v_mov_b32_e32 v118, v2
	v_mov_b32_e32 v119, v2
	v_mov_b32_e32 v120, v2
	v_mov_b32_e32 v121, v2
	v_mov_b32_e32 v126, v2
	v_mov_b32_e32 v127, v2
	v_mov_b32_e32 v128, v2
	v_mov_b32_e32 v129, v2
	v_mov_b32_e32 v62, v2
	v_mov_b32_e32 v63, v2
	v_mov_b32_e32 v64, v2
	v_mov_b32_e32 v65, v2
	v_mov_b32_e32 v54, v2
	v_mov_b32_e32 v55, v2
	v_mov_b32_e32 v56, v2
	v_mov_b32_e32 v57, v2
	v_mov_b32_e32 v46, v2
	v_mov_b32_e32 v47, v2
	v_mov_b32_e32 v48, v2
	v_mov_b32_e32 v49, v2
	v_mov_b32_e32 v38, v2
	v_mov_b32_e32 v39, v2
	v_mov_b32_e32 v40, v2
	v_mov_b32_e32 v41, v2
	v_mov_b32_e32 v26, v2
	v_mov_b32_e32 v27, v2
	v_mov_b32_e32 v28, v2
	v_mov_b32_e32 v29, v2
	v_mov_b32_e32 v22, v2
	v_mov_b32_e32 v23, v2
	v_mov_b32_e32 v24, v2
	v_mov_b32_e32 v25, v2
	v_mov_b32_e32 v34, v2
	v_mov_b32_e32 v35, v2
	v_mov_b32_e32 v36, v2
	v_mov_b32_e32 v37, v2
	v_mov_b32_e32 v18, v2
	v_mov_b32_e32 v19, v2
	v_mov_b32_e32 v20, v2
	v_mov_b32_e32 v21, v2
	s_waitcnt vmcnt(0) lgkmcnt(0)
	s_barrier
	s_branch .LBB0_1280
